# scan state-update stage: B-operand LDS reads now issued three MFMAs ahead over four rotating quads (lgkmcnt(6))
# baseline (speedup 1.0000x reference)
.LBB0_484:
	v_mov_b32_e32 v89, v106
	v_mov_b32_e32 v56, v105
	v_mov_b32_e32 v40, v104
	s_bfe_i32 s0, s42, 0x10000
	s_waitcnt lgkmcnt(0)
	s_barrier
	s_and_b32 s50, s42, 1
	s_and_b32 s49, s0, 0x17600
	s_add_i32 s42, s42, 1
	v_lshlrev_b32_e32 v41, 6, v40
	v_lshlrev_b32_e32 v40, 3, v40
	s_add_u32 s0, s43, s2
	v_and_b32_e32 v41, 0xfffffc00, v41
	v_and_b32_e32 v40, 0x78, v40
	s_addc_u32 s1, s48, s3
	v_or3_b32 v172, v41, v40, s39
	v_lshl_add_u64 v[44:45], v[172:173], 1, s[0:1]
	s_mov_b32 s0, 0x1c020000
	v_add_co_u32_e64 v40, s[0:1], s0, v44
	s_cmp_eq_u32 s50, 0
	s_nop 0
	v_addc_co_u32_e64 v41, s[0:1], 0, v45, s[0:1]
	s_mov_b32 s0, 0x1c030000
	global_load_dwordx4 v[48:51], v[40:41], off
	v_add_co_u32_e64 v40, s[0:1], s0, v44
	v_ashrrev_i32_e32 v57, 2, v56
	s_nop 0
	v_addc_co_u32_e64 v41, s[0:1], 0, v45, s[0:1]
	s_mov_b32 s0, 0x18020000
	global_load_dwordx4 v[52:55], v[40:41], off
	v_add_co_u32_e64 v40, s[0:1], s0, v44
	v_lshlrev_b32_e32 v56, 2, v56
	s_nop 0
	v_addc_co_u32_e64 v41, s[0:1], 0, v45, s[0:1]
	s_mov_b32 s0, 0x18030000
	s_nop 0
	v_add_co_u32_e64 v44, s[0:1], s0, v44
	s_cselect_b32 s50, 0x20200, s65
	s_nop 0
	v_addc_co_u32_e64 v45, s[0:1], 0, v45, s[0:1]
	v_and_b32_e32 v107, 12, v56
	s_cselect_b32 s1, 0x17600, 0
	s_cselect_b32 s0, s65, 0x20200
	s_add_i32 s50, s50, 0
	v_or_b32_e32 v56, s28, v107
	v_lshl_add_u32 v90, v89, 3, v57
	v_lshl_add_u32 v88, v56, 1, s50
	v_mad_u64_u32 v[58:59], s[50:51], v90, s61, v[88:89]
	v_lshlrev_b32_e32 v89, 2, v89
	v_sub_u32_e32 v132, v90, v89
	v_mad_u64_u32 v[88:89], s[50:51], v132, s61, v[88:89]
	global_load_dwordx4 v[40:43], v[40:41], off
	v_mov_b64_e32 v[110:111], s[46:47]
	global_load_dwordx4 v[44:47], v[44:45], off
	ds_read_b64_tr_b16 v[60:61], v58
	ds_read_b64_tr_b16 v[62:63], v58 offset:1088
	ds_read_b64_tr_b16 v[56:57], v58 offset:8704
	ds_read_b64_tr_b16 v[58:59], v58 offset:9792
	ds_read_b64_tr_b16 v[90:91], v88
	v_mov_b64_e32 v[108:109], s[44:45]
	s_waitcnt lgkmcnt(3)
	v_mfma_f32_16x16x32_bf16 v[116:119], v[4:7], v[60:63], 0
	s_add_i32 s1, s1, 0
	s_add_i32 s0, s0, 0
	s_waitcnt lgkmcnt(0)
	v_lshlrev_b32_e32 v89, 16, v90
	v_mul_f32_e32 v89, 0x3fb8aa3b, v89
	v_exp_f32_e32 v102, v89
	v_and_b32_e32 v89, 0xffff0000, v90
	v_mul_f32_e32 v89, 0x3fb8aa3b, v89
	v_exp_f32_e32 v103, v89
	v_lshlrev_b32_e32 v89, 16, v91
	v_mfma_f32_16x16x32_bf16 v[112:115], v[108:111], v[60:63], 0
	v_mul_f32_e32 v89, 0x3fb8aa3b, v89
	v_exp_f32_e32 v100, v89
	v_and_b32_e32 v89, 0xffff0000, v91
	ds_read_b64_tr_b16 v[90:91], v88 offset:4352
	v_mfma_f32_16x16x32_bf16 v[124:127], v[4:7], v[56:59], v[112:115]
	v_mul_f32_e32 v89, 0x3fb8aa3b, v89
	v_exp_f32_e32 v101, v89
	v_pk_add_f32 v[102:103], v[102:103], 1.0 op_sel_hi:[1,0] neg_lo:[1,0] neg_hi:[1,0]
	v_mfma_f32_16x16x32_bf16 v[128:131], v[0:3], v[56:59], v[112:115]
	s_waitcnt lgkmcnt(0)
	v_lshlrev_b32_e32 v89, 16, v90
	v_mul_f32_e32 v89, 0x3fb8aa3b, v89
	v_exp_f32_e32 v98, v89
	v_mfma_f32_16x16x32_bf16 v[112:115], v[108:111], v[56:59], v[112:115]
	v_and_b32_e32 v89, 0xffff0000, v90
	v_mul_f32_e32 v89, 0x3fb8aa3b, v89
	v_exp_f32_e32 v99, v89
	v_lshlrev_b32_e32 v89, 16, v91
	v_mul_f32_e32 v89, 0x3fb8aa3b, v89
	s_nop 2
	v_sub_f32_e32 v116, v112, v116
	v_sub_f32_e32 v117, v113, v117
	v_mul_f32_e32 v116, 0x3fb8aa3b, v116
	v_mul_f32_e32 v117, 0x3fb8aa3b, v117
	v_exp_f32_e32 v116, v116
	v_exp_f32_e32 v117, v117
	v_exp_f32_e32 v96, v89
	v_and_b32_e32 v89, 0xffff0000, v91
	ds_read_b64_tr_b16 v[90:91], v88 offset:8704
	v_pk_mul_f32 v[102:103], v[102:103], v[116:117]
	v_sub_f32_e32 v116, v114, v118
	v_sub_f32_e32 v117, v115, v119
	v_mul_f32_e32 v116, 0x3fb8aa3b, v116
	v_mul_f32_e32 v117, 0x3fb8aa3b, v117
	v_mfma_f32_16x16x32_bf16 v[120:123], v[0:3], v[60:63], 0
	v_exp_f32_e32 v116, v116
	v_exp_f32_e32 v117, v117
	v_mul_f32_e32 v89, 0x3fb8aa3b, v89
	v_exp_f32_e32 v97, v89
	s_waitcnt lgkmcnt(0)
	v_lshlrev_b32_e32 v89, 16, v90
	v_mul_f32_e32 v89, 0x3fb8aa3b, v89
	v_pk_add_f32 v[100:101], v[100:101], 1.0 op_sel_hi:[1,0] neg_lo:[1,0] neg_hi:[1,0]
	v_exp_f32_e32 v94, v89
	v_and_b32_e32 v89, 0xffff0000, v90
	v_pk_mul_f32 v[100:101], v[100:101], v[116:117]
	v_sub_f32_e32 v116, v112, v120
	v_sub_f32_e32 v117, v113, v121
	v_mul_f32_e32 v89, 0x3fb8aa3b, v89
	v_mul_f32_e32 v116, 0x3fb8aa3b, v116
	v_mul_f32_e32 v117, 0x3fb8aa3b, v117
	v_exp_f32_e32 v95, v89
	v_lshlrev_b32_e32 v89, 16, v91
	v_exp_f32_e32 v116, v116
	v_exp_f32_e32 v117, v117
	v_mul_f32_e32 v89, 0x3fb8aa3b, v89
	v_exp_f32_e32 v92, v89
	v_and_b32_e32 v89, 0xffff0000, v91
	v_mul_f32_e32 v89, 0x3fb8aa3b, v89
	v_pk_add_f32 v[98:99], v[98:99], 1.0 op_sel_hi:[1,0] neg_lo:[1,0] neg_hi:[1,0]
	v_exp_f32_e32 v93, v89
	ds_read_b64_tr_b16 v[88:89], v88 offset:13056
	v_pk_mul_f32 v[98:99], v[98:99], v[116:117]
	v_sub_f32_e32 v116, v114, v122
	v_sub_f32_e32 v117, v115, v123
	v_mul_f32_e32 v116, 0x3fb8aa3b, v116
	v_mul_f32_e32 v117, 0x3fb8aa3b, v117
	v_exp_f32_e32 v116, v116
	v_exp_f32_e32 v117, v117
	s_waitcnt lgkmcnt(0)
	v_lshlrev_b32_e32 v90, 16, v88
	v_and_b32_e32 v88, 0xffff0000, v88
	v_pk_add_f32 v[96:97], v[96:97], 1.0 op_sel_hi:[1,0] neg_lo:[1,0] neg_hi:[1,0]
	v_mul_f32_e32 v90, 0x3fb8aa3b, v90
	v_mul_f32_e32 v88, 0x3fb8aa3b, v88
	v_pk_mul_f32 v[96:97], v[96:97], v[116:117]
	v_sub_f32_e32 v116, v112, v124
	v_sub_f32_e32 v117, v113, v125
	v_sub_f32_e32 v112, v112, v128
	v_sub_f32_e32 v113, v113, v129
	v_exp_f32_e32 v90, v90
	v_exp_f32_e32 v91, v88
	v_mul_f32_e32 v112, 0x3fb8aa3b, v112
	v_mul_f32_e32 v113, 0x3fb8aa3b, v113
	v_exp_f32_e32 v112, v112
	v_exp_f32_e32 v113, v113
	v_mul_f32_e32 v116, 0x3fb8aa3b, v116
	v_mul_f32_e32 v117, 0x3fb8aa3b, v117
	v_mfma_f32_16x16x32_bf16 v[60:63], v[60:63], v[108:111], 0
	v_exp_f32_e32 v116, v116
	v_exp_f32_e32 v117, v117
	v_pk_add_f32 v[90:91], v[90:91], 1.0 op_sel_hi:[1,0] neg_lo:[1,0] neg_hi:[1,0]
	v_lshlrev_b32_e32 v88, 16, v89
	v_pk_mul_f32 v[112:113], v[90:91], v[112:113]
	v_sub_f32_e32 v90, v114, v130
	v_and_b32_e32 v89, 0xffff0000, v89
	v_pk_add_f32 v[94:95], v[94:95], 1.0 op_sel_hi:[1,0] neg_lo:[1,0] neg_hi:[1,0]
	v_mul_f32_e32 v90, 0x3fb8aa3b, v90
	v_mul_f32_e32 v88, 0x3fb8aa3b, v88
	v_mul_f32_e32 v89, 0x3fb8aa3b, v89
	v_pk_mul_f32 v[94:95], v[94:95], v[116:117]
	v_sub_f32_e32 v116, v114, v126
	v_sub_f32_e32 v117, v115, v127
	v_exp_f32_e32 v114, v90
	v_sub_f32_e32 v90, v115, v131
	v_mfma_f32_16x16x32_bf16 v[56:59], v[56:59], v[108:111], v[60:63]
	v_exp_f32_e32 v88, v88
	v_exp_f32_e32 v89, v89
	v_mul_f32_e32 v116, 0x3fb8aa3b, v116
	v_mul_f32_e32 v117, 0x3fb8aa3b, v117
	v_mul_f32_e32 v90, 0x3fb8aa3b, v90
	v_exp_f32_e32 v116, v116
	v_exp_f32_e32 v117, v117
	v_exp_f32_e32 v115, v90
	v_cvt_pk_bf16_f32 v90, v94, v95
	v_mul_f32_e32 v94, 0x3fb8aa3b, v58
	v_pk_add_f32 v[92:93], v[92:93], 1.0 op_sel_hi:[1,0] neg_lo:[1,0] neg_hi:[1,0]
	v_cvt_pk_bf16_f32 v60, v102, v103
	v_pk_add_f32 v[88:89], v[88:89], 1.0 op_sel_hi:[1,0] neg_lo:[1,0] neg_hi:[1,0]
	v_exp_f32_e32 v102, v94
	v_mul_f32_e32 v94, 0x3fb8aa3b, v59
	v_pk_mul_f32 v[92:93], v[92:93], v[116:117]
	v_pk_mul_f32 v[88:89], v[88:89], v[114:115]
	v_exp_f32_e32 v103, v94
	v_lshlrev_b32_e32 v94, 1, v107
	v_mul_lo_u32 v95, v132, s20
	v_cvt_pk_bf16_f32 v91, v92, v93
	v_cvt_pk_bf16_f32 v93, v88, v89
	v_mul_f32_e32 v88, 0x3fb8aa3b, v56
	v_mul_f32_e32 v89, 0x3fb8aa3b, v57
	v_add3_u32 v107, s1, v94, v95
	v_cvt_pk_bf16_f32 v61, v100, v101
	v_cvt_pk_bf16_f32 v62, v98, v99
	v_cvt_pk_bf16_f32 v63, v96, v97
	v_exp_f32_e32 v88, v88
	v_exp_f32_e32 v89, v89
	ds_read_b64_tr_b16 v[94:95], v107
	ds_read_b64_tr_b16 v[98:99], v107 offset:32
	ds_read_b64_tr_b16 v[96:97], v107 offset:4608
	v_pk_mul_f32 v[38:39], v[38:39], v[102:103]
	v_cvt_pk_bf16_f32 v92, v112, v113
	v_pk_mul_f32 v[36:37], v[36:37], v[88:89]
	v_pk_mul_f32 v[34:35], v[34:35], v[102:103]
	v_pk_mul_f32 v[32:33], v[32:33], v[88:89]
	s_waitcnt lgkmcnt(0)
	v_mfma_f32_16x16x32_bf16 v[36:39], v[60:63], v[94:97], v[36:39]
	ds_read_b64_tr_b16 v[94:95], v107 offset:9216
	ds_read_b64_tr_b16 v[96:97], v107 offset:13824
	ds_read_b64_tr_b16 v[100:101], v107 offset:4640
	v_pk_mul_f32 v[30:31], v[30:31], v[102:103]
	s_waitcnt lgkmcnt(1)
	v_mfma_f32_16x16x32_bf16 v[36:39], v[90:93], v[94:97], v[36:39]
	ds_read_b64_tr_b16 v[94:95], v107 offset:9248
	ds_read_b64_tr_b16 v[96:97], v107 offset:13856
	v_pk_mul_f32 v[28:29], v[28:29], v[88:89]
	v_pk_mul_f32 v[26:27], v[26:27], v[102:103]
	s_waitcnt lgkmcnt(2)
	v_mfma_f32_16x16x32_bf16 v[32:35], v[60:63], v[98:101], v[32:35]
	v_mul_f32_e64 v24, v24, v88
	v_mul_f32_e64 v25, v25, v89
	v_pk_mul_f32 v[22:23], v[22:23], v[102:103]
	v_pk_mul_f32 v[20:21], v[20:21], v[88:89]
	s_waitcnt lgkmcnt(0)
	v_mfma_f32_16x16x32_bf16 v[32:35], v[90:93], v[94:97], v[32:35]
	ds_read_b64_tr_b16 v[94:95], v107 offset:64
	ds_read_b64_tr_b16 v[96:97], v107 offset:4672
	ds_read_b64_tr_b16 v[228:229], v107 offset:9280
	ds_read_b64_tr_b16 v[230:231], v107 offset:13888
	ds_read_b64_tr_b16 v[232:233], v107 offset:96
	ds_read_b64_tr_b16 v[234:235], v107 offset:4704
	ds_read_b64_tr_b16 v[236:237], v107 offset:9312
	ds_read_b64_tr_b16 v[238:239], v107 offset:13920
	v_pk_mul_f32 v[18:19], v[18:19], v[102:103]
	v_pk_mul_f32 v[16:17], v[16:17], v[88:89]
	s_waitcnt lgkmcnt(6)
	v_mfma_f32_16x16x32_bf16 v[28:31], v[60:63], v[94:97], v[28:31]
	ds_read_b64_tr_b16 v[94:95], v107 offset:128
	ds_read_b64_tr_b16 v[96:97], v107 offset:4736
	v_pk_mul_f32 v[14:15], v[14:15], v[102:103]
	v_pk_mul_f32 v[12:13], v[12:13], v[88:89]
	s_waitcnt lgkmcnt(6)
	v_mfma_f32_16x16x32_bf16 v[28:31], v[90:93], v[228:231], v[28:31]
	ds_read_b64_tr_b16 v[228:229], v107 offset:9344
	ds_read_b64_tr_b16 v[230:231], v107 offset:13952
	v_pk_mul_f32 v[10:11], v[10:11], v[102:103]
	v_pk_mul_f32 v[8:9], v[8:9], v[88:89]
	s_waitcnt lgkmcnt(6)
	v_mfma_f32_16x16x32_bf16 v[24:27], v[60:63], v[232:235], v[24:27]
	ds_read_b64_tr_b16 v[232:233], v107 offset:160
	ds_read_b64_tr_b16 v[234:235], v107 offset:4768
	v_pk_add_f32 v[84:85], v[84:85], v[56:57]
	v_mov_b32_e32 v56, v104
	s_waitcnt lgkmcnt(6)
	v_mfma_f32_16x16x32_bf16 v[24:27], v[90:93], v[236:239], v[24:27]
	ds_read_b64_tr_b16 v[236:237], v107 offset:9376
	ds_read_b64_tr_b16 v[238:239], v107 offset:13984
	v_pk_add_f32 v[86:87], v[86:87], v[58:59]
	s_add_i32 s1, s49, 0
	s_waitcnt lgkmcnt(6)
	v_mfma_f32_16x16x32_bf16 v[20:23], v[60:63], v[94:97], v[20:23]
	ds_read_b64_tr_b16 v[94:95], v107 offset:192
	ds_read_b64_tr_b16 v[96:97], v107 offset:4800
	s_add_u32 s2, s2, 0x20000
	s_addc_u32 s3, s3, 0
	s_waitcnt lgkmcnt(6)
	v_mfma_f32_16x16x32_bf16 v[20:23], v[90:93], v[228:231], v[20:23]
	ds_read_b64_tr_b16 v[228:229], v107 offset:9408
	ds_read_b64_tr_b16 v[230:231], v107 offset:14016
	s_cmp_eq_u32 s2, 0x1e0000
	s_waitcnt lgkmcnt(6)
	v_mfma_f32_16x16x32_bf16 v[16:19], v[60:63], v[232:235], v[16:19]
	ds_read_b64_tr_b16 v[232:233], v107 offset:224
	ds_read_b64_tr_b16 v[234:235], v107 offset:4832
	s_waitcnt lgkmcnt(6)
	v_mfma_f32_16x16x32_bf16 v[16:19], v[90:93], v[236:239], v[16:19]
	s_waitcnt lgkmcnt(4)
	v_mfma_f32_16x16x32_bf16 v[12:15], v[60:63], v[94:97], v[12:15]
	s_waitcnt lgkmcnt(2)
	v_mfma_f32_16x16x32_bf16 v[12:15], v[90:93], v[228:231], v[12:15]
	s_waitcnt lgkmcnt(0)
	v_mfma_f32_16x16x32_bf16 v[8:11], v[60:63], v[232:235], v[8:11]
	ds_read_b64_tr_b16 v[60:61], v107 offset:9440
	ds_read_b64_tr_b16 v[62:63], v107 offset:14048
	s_nop 0
	v_ashrrev_i32_e32 v57, 4, v56
	v_lshlrev_b32_e32 v56, 4, v56
	s_waitcnt lgkmcnt(0)
	v_mfma_f32_16x16x32_bf16 v[8:11], v[90:93], v[60:63], v[8:11]
	v_mul_lo_u32 v58, v57, s20
	v_and_b32_e32 v56, 0xf0, v56
	v_add3_u32 v58, s1, v58, v56
	s_waitcnt vmcnt(3)
	ds_write_b128 v58, v[48:51]
	s_waitcnt vmcnt(2)
	ds_write_b128 v58, v[52:55] offset:9216
	v_mul_lo_u32 v48, v57, s61
	v_add3_u32 v48, s0, v48, v56
	s_waitcnt vmcnt(1)
	ds_write_b128 v48, v[40:43]
	s_waitcnt vmcnt(0)
	ds_write_b128 v48, v[44:47] offset:8704
	s_cbranch_scc0 .LBB0_484
	v_mov_b32_e32 v40, v105
	v_mov_b32_e32 v41, v106
	v_mov_b32_e32 v107, v104
	v_ashrrev_i32_e32 v42, 2, v40
	v_lshlrev_b32_e32 v40, 2, v40
	v_and_b32_e32 v116, 12, v40
	v_or_b32_e32 v40, s28, v116
	v_lshl_add_u32 v42, v41, 3, v42
	v_lshl_add_u32 v40, v40, 1, 0
	v_mad_u64_u32 v[46:47], s[0:1], v42, s61, v[40:41]
	v_lshlrev_b32_e32 v41, 2, v41
	v_sub_u32_e32 v117, v42, v41
	v_mad_u64_u32 v[48:49], s[0:1], v117, s61, v[40:41]
	s_waitcnt lgkmcnt(0)
	s_barrier
	ds_read_b64_tr_b16 v[50:51], v48 offset:18432
	ds_read_b64_tr_b16 v[40:41], v46 offset:18432
	ds_read_b64_tr_b16 v[42:43], v46 offset:19520
	ds_read_b64_tr_b16 v[44:45], v46 offset:27136
	ds_read_b64_tr_b16 v[46:47], v46 offset:28224
	ds_read_b64_tr_b16 v[52:53], v48 offset:22784
	ds_read_b64_tr_b16 v[60:61], v48 offset:27136
	ds_read_b64_tr_b16 v[96:97], v48 offset:31488
	s_waitcnt lgkmcnt(7)
	v_lshlrev_b32_e32 v48, 16, v50
	v_mul_f32_e32 v48, 0x3fb8aa3b, v48
	v_exp_f32_e32 v98, v48
	v_and_b32_e32 v48, 0xffff0000, v50
	v_mul_f32_e32 v48, 0x3fb8aa3b, v48
	v_exp_f32_e32 v99, v48
	v_lshlrev_b32_e32 v48, 16, v51
	v_mul_f32_e32 v48, 0x3fb8aa3b, v48
	v_exp_f32_e32 v100, v48
	v_and_b32_e32 v48, 0xffff0000, v51
	v_mul_f32_e32 v48, 0x3fb8aa3b, v48
	v_exp_f32_e32 v101, v48
	s_waitcnt lgkmcnt(2)
	v_lshlrev_b32_e32 v48, 16, v52
	v_mul_f32_e32 v48, 0x3fb8aa3b, v48
	v_exp_f32_e32 v102, v48
	v_and_b32_e32 v48, 0xffff0000, v52
	v_mul_f32_e32 v48, 0x3fb8aa3b, v48
	v_exp_f32_e32 v103, v48
	v_lshlrev_b32_e32 v48, 16, v53
	v_mul_f32_e32 v48, 0x3fb8aa3b, v48
	v_exp_f32_e32 v108, v48
	v_and_b32_e32 v48, 0xffff0000, v53
	v_mul_f32_e32 v48, 0x3fb8aa3b, v48
	v_exp_f32_e32 v109, v48
	s_waitcnt lgkmcnt(1)
	v_lshlrev_b32_e32 v48, 16, v60
	v_mul_f32_e32 v52, 0x3fb8aa3b, v48
	v_mov_b64_e32 v[50:51], s[46:47]
	v_mov_b64_e32 v[48:49], s[44:45]
	v_exp_f32_e32 v110, v52
	v_and_b32_e32 v52, 0xffff0000, v60
	v_mul_f32_e32 v52, 0x3fb8aa3b, v52
	v_exp_f32_e32 v111, v52
	v_mfma_f32_16x16x32_bf16 v[52:55], v[48:51], v[40:43], 0
	v_lshlrev_b32_e32 v56, 16, v61
	v_and_b32_e32 v60, 0xffff0000, v61
	s_waitcnt lgkmcnt(0)
	v_lshlrev_b32_e32 v88, 16, v96
	v_and_b32_e32 v92, 0xffff0000, v96
	v_mul_f32_e32 v56, 0x3fb8aa3b, v56
	v_mul_f32_e32 v60, 0x3fb8aa3b, v60
	v_mul_f32_e32 v88, 0x3fb8aa3b, v88
	v_mul_f32_e32 v92, 0x3fb8aa3b, v92
	v_exp_f32_e32 v112, v56
	v_mfma_f32_16x16x32_bf16 v[56:59], v[4:7], v[40:43], 0
	v_exp_f32_e32 v113, v60
	v_exp_f32_e32 v114, v88
	v_exp_f32_e32 v115, v92
	v_mfma_f32_16x16x32_bf16 v[60:63], v[0:3], v[40:43], 0
	v_lshlrev_b32_e32 v96, 16, v97
	v_and_b32_e32 v97, 0xffff0000, v97
	v_mul_f32_e32 v96, 0x3fb8aa3b, v96
	v_mfma_f32_16x16x32_bf16 v[88:91], v[4:7], v[44:47], v[52:55]
	v_mul_f32_e32 v97, 0x3fb8aa3b, v97
	v_exp_f32_e32 v96, v96
	v_exp_f32_e32 v97, v97
	v_mfma_f32_16x16x32_bf16 v[92:95], v[0:3], v[44:47], v[52:55]
	v_add_f32_e64 v100, -v100, 1.0
	v_add_f32_e64 v101, -v101, 1.0
	s_lshl_b64 s[0:1], s[30:31], 1
	s_or_b32 s0, s0, 0x1e0000
	v_mfma_f32_16x16x32_bf16 v[52:55], v[48:51], v[44:47], v[52:55]
	s_add_u32 s2, s36, s0
	s_addc_u32 s3, s37, s1
	s_add_u32 s30, s34, s0
	v_mfma_f32_16x16x32_bf16 v[40:43], v[40:43], v[48:51], 0
	s_addc_u32 s31, s35, s1
	s_nop 2
	v_sub_f32_e32 v56, v52, v56
	v_sub_f32_e32 v57, v53, v57
	v_sub_f32_e32 v58, v54, v58
	v_sub_f32_e32 v59, v55, v59
	v_sub_f32_e32 v60, v52, v60
	v_sub_f32_e32 v61, v53, v61
	v_sub_f32_e32 v88, v52, v88
	v_sub_f32_e32 v89, v53, v89
	v_sub_f32_e32 v52, v52, v92
	v_sub_f32_e32 v53, v53, v93
	v_mul_f32_e32 v58, 0x3fb8aa3b, v58
	v_mul_f32_e32 v59, 0x3fb8aa3b, v59
	v_sub_f32_e32 v62, v54, v62
	v_sub_f32_e32 v63, v55, v63
	v_sub_f32_e32 v90, v54, v90
	v_sub_f32_e32 v91, v55, v91
	v_mul_f32_e32 v52, 0x3fb8aa3b, v52
	v_mul_f32_e32 v53, 0x3fb8aa3b, v53
	v_sub_f32_e32 v54, v54, v94
	v_sub_f32_e32 v55, v55, v95
	v_exp_f32_e32 v58, v58
	v_exp_f32_e32 v59, v59
	v_mul_f32_e32 v60, 0x3fb8aa3b, v60
	v_mul_f32_e32 v61, 0x3fb8aa3b, v61
	v_exp_f32_e32 v52, v52
	v_exp_f32_e32 v53, v53
	v_mul_f32_e32 v54, 0x3fb8aa3b, v54
	v_mul_f32_e32 v55, 0x3fb8aa3b, v55
	v_mul_f32_e32 v56, 0x3fb8aa3b, v56
	v_mul_f32_e32 v57, 0x3fb8aa3b, v57
	v_exp_f32_e32 v60, v60
	v_exp_f32_e32 v61, v61
	v_mul_f32_e32 v62, 0x3fb8aa3b, v62
	v_mul_f32_e32 v63, 0x3fb8aa3b, v63
	v_exp_f32_e32 v54, v54
	v_exp_f32_e32 v55, v55
	v_exp_f32_e32 v56, v56
	v_exp_f32_e32 v57, v57
	v_exp_f32_e32 v62, v62
	v_exp_f32_e32 v63, v63
	v_mfma_f32_16x16x32_bf16 v[40:43], v[44:47], v[48:51], v[40:43]
	v_add_f32_e64 v92, -v114, 1.0
	v_add_f32_e64 v93, -v115, 1.0
	v_pk_mul_f32 v[58:59], v[100:101], v[58:59]
	v_pk_add_f32 v[100:101], v[102:103], 1.0 op_sel_hi:[1,0] neg_lo:[1,0] neg_hi:[1,0]
	v_mul_f32_e32 v88, 0x3fb8aa3b, v88
	v_mul_f32_e32 v89, 0x3fb8aa3b, v89
	v_pk_mul_f32 v[52:53], v[92:93], v[52:53]
	v_pk_add_f32 v[92:93], v[96:97], 1.0 op_sel_hi:[1,0] neg_lo:[1,0] neg_hi:[1,0]
	v_pk_mul_f32 v[60:61], v[100:101], v[60:61]
	v_pk_add_f32 v[100:101], v[108:109], 1.0 op_sel_hi:[1,0] neg_lo:[1,0] neg_hi:[1,0]
	v_exp_f32_e32 v88, v88
	v_exp_f32_e32 v89, v89
	v_mul_f32_e32 v90, 0x3fb8aa3b, v90
	v_mul_f32_e32 v91, 0x3fb8aa3b, v91
	v_pk_mul_f32 v[54:55], v[92:93], v[54:55]
	v_pk_add_f32 v[44:45], v[98:99], 1.0 op_sel_hi:[1,0] neg_lo:[1,0] neg_hi:[1,0]
	v_pk_mul_f32 v[62:63], v[100:101], v[62:63]
	v_exp_f32_e32 v90, v90
	v_exp_f32_e32 v91, v91
	v_pk_mul_f32 v[44:45], v[44:45], v[56:57]
	v_cvt_pk_bf16_f32 v46, v52, v53
	v_cvt_pk_bf16_f32 v47, v54, v55
	v_mul_f32_e32 v52, 0x3fb8aa3b, v40
	v_mul_f32_e32 v53, 0x3fb8aa3b, v41
	v_mul_f32_e32 v54, 0x3fb8aa3b, v42
	v_mul_f32_e32 v55, 0x3fb8aa3b, v43
	v_cvt_pk_bf16_f32 v48, v44, v45
	v_cvt_pk_bf16_f32 v49, v58, v59
	v_cvt_pk_bf16_f32 v50, v60, v61
	v_cvt_pk_bf16_f32 v51, v62, v63
	v_exp_f32_e32 v52, v52
	v_exp_f32_e32 v54, v54
	v_exp_f32_e32 v55, v55
	v_exp_f32_e32 v53, v53
	v_pk_add_f32 v[100:101], v[110:111], 1.0 op_sel_hi:[1,0] neg_lo:[1,0] neg_hi:[1,0]
	v_lshlrev_b32_e32 v56, 1, v116
	v_pk_mul_f32 v[88:89], v[100:101], v[88:89]
	v_pk_add_f32 v[100:101], v[112:113], 1.0 op_sel_hi:[1,0] neg_lo:[1,0] neg_hi:[1,0]
	v_mul_lo_u32 v57, v117, s20
	v_pk_mul_f32 v[90:91], v[100:101], v[90:91]
	v_cvt_pk_bf16_f32 v44, v88, v89
	v_cvt_pk_bf16_f32 v45, v90, v91
	v_pk_mul_f32 v[38:39], v[38:39], v[54:55]
	v_pk_mul_f32 v[36:37], v[36:37], v[52:53]
	v_add3_u32 v112, 0, v56, v57
	ds_read_b64_tr_b16 v[58:59], v112 offset:4608
	ds_read_b64_tr_b16 v[56:57], v112
	ds_read_b64_tr_b16 v[60:61], v112 offset:32
	ds_read_b64_tr_b16 v[88:89], v112 offset:64
	ds_read_b64_tr_b16 v[92:93], v112 offset:96
	ds_read_b64_tr_b16 v[62:63], v112 offset:4640
	ds_read_b64_tr_b16 v[90:91], v112 offset:4672
	ds_read_b64_tr_b16 v[94:95], v112 offset:4704
	s_waitcnt lgkmcnt(6)
	v_mfma_f32_16x16x32_bf16 v[36:39], v[48:51], v[56:59], v[36:39]
	ds_read_b64_tr_b16 v[58:59], v112 offset:13824
	ds_read_b64_tr_b16 v[56:57], v112 offset:9216
	ds_read_b64_tr_b16 v[96:97], v112 offset:9248
	ds_read_b64_tr_b16 v[100:101], v112 offset:9280
	ds_read_b64_tr_b16 v[108:109], v112 offset:9312
	ds_read_b64_tr_b16 v[98:99], v112 offset:13856
	ds_read_b64_tr_b16 v[102:103], v112 offset:13888
	ds_read_b64_tr_b16 v[110:111], v112 offset:13920
	v_pk_mul_f32 v[34:35], v[34:35], v[54:55]
	v_pk_mul_f32 v[32:33], v[32:33], v[52:53]
	s_waitcnt lgkmcnt(6)
	v_mfma_f32_16x16x32_bf16 v[36:39], v[44:47], v[56:59], v[36:39]
	v_lshlrev_b32_e32 v56, 6, v107
	v_pk_mul_f32 v[30:31], v[30:31], v[54:55]
	v_pk_mul_f32 v[28:29], v[28:29], v[52:53]
	v_lshlrev_b32_e32 v57, 3, v107
	v_pk_mul_f32 v[26:27], v[26:27], v[54:55]
	v_pk_mul_f32 v[24:25], v[24:25], v[52:53]
	v_mfma_f32_16x16x32_bf16 v[32:35], v[48:51], v[60:63], v[32:35]
	v_and_b32_e32 v56, 0xfffffc00, v56
	v_and_b32_e32 v57, 0x78, v57
	v_pk_mul_f32 v[22:23], v[22:23], v[54:55]
	v_mfma_f32_16x16x32_bf16 v[28:31], v[48:51], v[88:91], v[28:31]
	v_mul_f32_e64 v20, v20, v52
	v_mul_f32_e64 v21, v21, v53
	v_or3_b32 v172, v56, v57, s39
	v_pk_mul_f32 v[18:19], v[18:19], v[54:55]
	v_mfma_f32_16x16x32_bf16 v[24:27], v[48:51], v[92:95], v[24:27]
	ds_read_b64_tr_b16 v[58:59], v112 offset:4736
	ds_read_b64_tr_b16 v[56:57], v112 offset:128
	ds_read_b64_tr_b16 v[60:61], v112 offset:160
	ds_read_b64_tr_b16 v[88:89], v112 offset:192
	ds_read_b64_tr_b16 v[92:93], v112 offset:224
	ds_read_b64_tr_b16 v[62:63], v112 offset:4768
	ds_read_b64_tr_b16 v[90:91], v112 offset:4800
	ds_read_b64_tr_b16 v[94:95], v112 offset:4832
	v_pk_mul_f32 v[16:17], v[16:17], v[52:53]
	v_pk_mul_f32 v[14:15], v[14:15], v[54:55]
	s_waitcnt lgkmcnt(6)
	v_mfma_f32_16x16x32_bf16 v[20:23], v[48:51], v[56:59], v[20:23]
	v_mul_f32_e64 v12, v12, v52
	v_mul_f32_e64 v13, v13, v53
	v_pk_mul_f32 v[10:11], v[10:11], v[54:55]
	v_pk_mul_f32 v[8:9], v[8:9], v[52:53]
	v_mfma_f32_16x16x32_bf16 v[32:35], v[44:47], v[96:99], v[32:35]
	v_mfma_f32_16x16x32_bf16 v[28:31], v[44:47], v[100:103], v[28:31]
	v_mfma_f32_16x16x32_bf16 v[24:27], v[44:47], v[108:111], v[24:27]
	ds_read_b64_tr_b16 v[58:59], v112 offset:13952
	ds_read_b64_tr_b16 v[56:57], v112 offset:9344
	ds_read_b64_tr_b16 v[96:97], v112 offset:9376
	ds_read_b64_tr_b16 v[100:101], v112 offset:9408
	ds_read_b64_tr_b16 v[108:109], v112 offset:9440
	ds_read_b64_tr_b16 v[98:99], v112 offset:13984
	ds_read_b64_tr_b16 v[102:103], v112 offset:14016
	ds_read_b64_tr_b16 v[110:111], v112 offset:14048
	v_lshlrev_b64 v[112:113], 1, v[172:173]
	s_waitcnt lgkmcnt(6)
	v_mfma_f32_16x16x32_bf16 v[20:23], v[44:47], v[56:59], v[20:23]
	v_lshl_add_u64 v[56:57], s[2:3], 0, v[112:113]
	v_mfma_f32_16x16x32_bf16 v[16:19], v[48:51], v[60:63], v[16:19]
	v_add_co_u32_e64 v60, s[0:1], s21, v56
	s_nop 1
	v_addc_co_u32_e64 v61, s[0:1], 0, v57, s[0:1]
	v_mfma_f32_16x16x32_bf16 v[12:15], v[48:51], v[88:91], v[12:15]
	v_lshl_add_u64 v[88:89], s[30:31], 0, v[112:113]
	v_add_co_u32_e64 v90, s[0:1], s21, v88
	global_load_dwordx4 v[56:59], v[56:57], off
	s_nop 0
	global_load_dwordx4 v[60:63], v[60:61], off
	v_addc_co_u32_e64 v91, s[0:1], 0, v89, s[0:1]
	v_mfma_f32_16x16x32_bf16 v[8:11], v[48:51], v[92:95], v[8:11]
	global_load_dwordx4 v[48:51], v[88:89], off
	global_load_dwordx4 v[52:55], v[90:91], off
	s_lshl_b32 s0, s38, 2
	s_or_b32 s0, s0, s29
	s_waitcnt lgkmcnt(2)
	v_mfma_f32_16x16x32_bf16 v[16:19], v[44:47], v[96:99], v[16:19]
	s_ashr_i32 s1, s0, 31
	s_lshl_b64 s[2:3], s[0:1], 16
	s_add_u32 s2, s18, s2
	s_waitcnt lgkmcnt(1)
	v_mfma_f32_16x16x32_bf16 v[12:15], v[44:47], v[100:103], v[12:15]
	s_addc_u32 s3, s19, s3
	s_waitcnt lgkmcnt(0)
	v_mfma_f32_16x16x32_bf16 v[8:11], v[44:47], v[108:111], v[8:11]
	v_mov_b32_e32 v44, v104
	s_nop 0
	v_ashrrev_i32_e32 v45, 4, v44
	v_lshlrev_b32_e32 v44, 4, v44
	v_mul_lo_u32 v46, v45, s20
	v_and_b32_e32 v44, 0xf0, v44
	v_mul_lo_u32 v45, v45, s61
	v_add3_u32 v46, s60, v46, v44
	v_add3_u32 v44, s64, v45, v44
	s_waitcnt vmcnt(3)
	ds_write_b128 v46, v[56:59]
	s_waitcnt vmcnt(2)
	ds_write_b128 v46, v[60:63] offset:9216
	s_waitcnt vmcnt(1)
	ds_write_b128 v44, v[48:51]
	s_waitcnt vmcnt(0)
	ds_write_b128 v44, v[52:55] offset:8704
	v_lshl_add_u64 v[44:45], v[66:67], 2, s[2:3]
	global_store_dword v[44:45], v36, off
	v_lshl_add_u64 v[44:45], v[68:69], 2, s[2:3]
	global_store_dword v[44:45], v37, off offset:512
	global_store_dword v[44:45], v38, off offset:1024
	global_store_dword v[44:45], v39, off offset:1536
	global_store_dword v[44:45], v32, off offset:64
	v_lshl_add_u64 v[36:37], v[70:71], 2, s[2:3]
	global_store_dword v[36:37], v33, off offset:512
	global_store_dword v[36:37], v34, off offset:1024
	global_store_dword v[36:37], v35, off offset:1536
	global_store_dword v[44:45], v28, off offset:128
	v_lshl_add_u64 v[32:33], v[72:73], 2, s[2:3]
	global_store_dword v[32:33], v29, off offset:512
	global_store_dword v[32:33], v30, off offset:1024
	global_store_dword v[32:33], v31, off offset:1536
	global_store_dword v[44:45], v24, off offset:192
	v_lshl_add_u64 v[28:29], v[74:75], 2, s[2:3]
	global_store_dword v[28:29], v25, off offset:512
	global_store_dword v[28:29], v26, off offset:1024
	global_store_dword v[28:29], v27, off offset:1536
	global_store_dword v[44:45], v20, off offset:256
	v_lshl_add_u64 v[24:25], v[76:77], 2, s[2:3]
	global_store_dword v[24:25], v21, off offset:512
	global_store_dword v[24:25], v22, off offset:1024
	global_store_dword v[24:25], v23, off offset:1536
	global_store_dword v[44:45], v16, off offset:320
	v_lshl_add_u64 v[20:21], v[78:79], 2, s[2:3]
	global_store_dword v[20:21], v17, off offset:512
	global_store_dword v[20:21], v18, off offset:1024
	global_store_dword v[20:21], v19, off offset:1536
	global_store_dword v[44:45], v12, off offset:384
	v_lshl_add_u64 v[16:17], v[80:81], 2, s[2:3]
	global_store_dword v[16:17], v13, off offset:512
	global_store_dword v[16:17], v14, off offset:1024
	global_store_dword v[16:17], v15, off offset:1536
	global_store_dword v[44:45], v8, off offset:448
	v_lshl_add_u64 v[12:13], v[82:83], 2, s[2:3]
	global_store_dword v[12:13], v9, off offset:512
	global_store_dword v[12:13], v10, off offset:1024
	global_store_dword v[12:13], v11, off offset:1536
	s_and_saveexec_b64 s[2:3], vcc
	s_cbranch_execz .LBB0_482
	v_pk_add_f32 v[10:11], v[86:87], v[42:43]
	v_pk_add_f32 v[8:9], v[84:85], v[40:41]
	v_mul_f32_e32 v10, 0x3fb8aa3b, v10
	v_mul_f32_e32 v8, 0x3fb8aa3b, v8
	v_mul_f32_e32 v9, 0x3fb8aa3b, v9
	v_mul_f32_e32 v11, 0x3fb8aa3b, v11
	v_exp_f32_e32 v8, v8
	v_exp_f32_e32 v9, v9
	v_exp_f32_e32 v10, v10
	v_exp_f32_e32 v11, v11
	s_lshl_b64 s[0:1], s[0:1], 9
	v_lshl_add_u64 v[12:13], v[64:65], 0, s[0:1]
	global_store_dwordx4 v[12:13], v[8:11], off
	s_branch .LBB0_482

.LBB0_606:
	s_mov_b32 s0, s94
	s_add_i32 s94, s94, 1
	s_lshl_b32 s1, s94, 6
	s_cmp_lg_u32 s0, 15
	s_cselect_b32 s0, s1, 0x3c0
	s_add_u32 s0, s48, s0
	v_mov_b32_e32 v128, v165
	v_mov_b32_e32 v187, v166
	s_addc_u32 s1, s49, 0
	v_mov_b32_e32 v44, v164
	s_waitcnt lgkmcnt(0)
	s_barrier
	s_lshl_b64 s[0:1], s[0:1], 11
	v_lshlrev_b32_e32 v45, 6, v44
	v_lshlrev_b32_e32 v44, 3, v44
	s_add_u32 s30, s70, s0
	v_and_b32_e32 v45, 0xfffffc00, v45
	v_and_b32_e32 v44, 0x78, v44
	s_addc_u32 s31, s71, s1
	v_or3_b32 v172, v45, v44, s93
	s_add_u32 s36, s80, s0
	s_addc_u32 s37, s81, s1
	v_lshlrev_b64 v[56:57], 1, v[172:173]
	v_lshl_add_u64 v[48:49], s[30:31], 0, v[56:57]
	v_lshl_add_u64 v[58:59], s[36:37], 0, v[56:57]
	global_load_dwordx4 v[44:47], v[48:49], off
	global_load_dwordx4 v[52:55], v[58:59], off
	v_add_co_u32_e32 v48, vcc, s21, v48
	s_add_u32 s0, s72, s0
	s_nop 0
	v_addc_co_u32_e32 v49, vcc, 0, v49, vcc
	v_lshlrev_b32_e32 v68, 2, v128
	s_addc_u32 s1, s73, s1
	v_add_co_u32_e32 v58, vcc, s21, v58
	v_ashrrev_i32_e32 v188, 2, v128
	v_and_b32_e32 v189, 12, v68
	v_addc_co_u32_e32 v59, vcc, 0, v59, vcc
	v_lshl_add_u64 v[60:61], s[0:1], 0, v[56:57]
	v_lshl_add_u32 v73, v187, 3, v188
	v_or_b32_e32 v68, s42, v189
	v_lshlrev_b32_e32 v130, 2, v187
	global_load_dwordx4 v[48:51], v[48:49], off
	v_lshl_add_u32 v72, v68, 1, s64
	global_load_dwordx4 v[64:67], v[58:59], off
	v_sub_u32_e32 v190, v73, v130
	global_load_dwordx4 v[56:59], v[60:61], off
	v_add_co_u32_e32 v60, vcc, s21, v60
	v_mad_u64_u32 v[74:75], s[0:1], v73, s61, v[72:73]
	s_nop 0
	v_addc_co_u32_e32 v61, vcc, 0, v61, vcc
	v_mad_u64_u32 v[72:73], s[0:1], v190, s61, v[72:73]
	global_load_dwordx4 v[60:63], v[60:61], off
	ds_read_b64_tr_b16 v[68:69], v74
	ds_read_b64_tr_b16 v[70:71], v74 offset:1088
	ds_read_b64_tr_b16 v[76:77], v74 offset:8704
	ds_read_b64_tr_b16 v[78:79], v74 offset:9792
	ds_read_b64_tr_b16 v[74:75], v72
	v_lshlrev_b32_e32 v82, 1, v128
	v_add_u32_e32 v80, s42, v130
	v_lshlrev_b32_e32 v172, 1, v80
	v_mul_lo_u32 v185, v128, s61
	s_waitcnt lgkmcnt(0)
	v_lshlrev_b32_e32 v73, 16, v74
	v_mul_f32_e32 v73, 0x3fb8aa3b, v73
	v_exp_f32_e32 v150, v73
	v_and_b32_e32 v73, 0xffff0000, v74
	v_mul_f32_e32 v73, 0x3fb8aa3b, v73
	v_exp_f32_e32 v151, v73
	v_lshlrev_b32_e32 v73, 16, v75
	v_mul_f32_e32 v73, 0x3fb8aa3b, v73
	v_exp_f32_e32 v148, v73
	v_and_b32_e32 v73, 0xffff0000, v75
	v_mul_f32_e32 v73, 0x3fb8aa3b, v73
	v_exp_f32_e32 v149, v73
	v_and_b32_e32 v73, 0x70, v82
	v_add_lshl_u32 v73, v73, v80, 1
	v_and_b32_e32 v73, 0xf8, v73
	v_add_u32_e32 v81, s64, v172
	v_add3_u32 v73, s66, v185, v73
	ds_read_b64 v[146:147], v73
	v_add_u32_e32 v73, v81, v185
	ds_read_b64 v[140:141], v73
	ds_read_b64_tr_b16 v[74:75], v72 offset:4352
	v_add_u32_e32 v129, 0x1100, v185
	v_add_u32_e32 v186, 0x2200, v185
	v_add_u32_e32 v131, 0x3300, v185
	v_mfma_f32_16x16x32_bf16 v[192:195], v[4:7], v[68:71], 0
	s_waitcnt lgkmcnt(0)
	v_lshlrev_b32_e32 v73, 16, v74
	v_mul_f32_e32 v73, 0x3fb8aa3b, v73
	v_exp_f32_e32 v154, v73
	v_and_b32_e32 v73, 0xffff0000, v74
	v_mul_f32_e32 v73, 0x3fb8aa3b, v73
	v_exp_f32_e32 v155, v73
	v_lshlrev_b32_e32 v73, 16, v75
	v_mul_f32_e32 v73, 0x3fb8aa3b, v73
	v_exp_f32_e32 v152, v73
	v_and_b32_e32 v73, 0xffff0000, v75
	v_mul_f32_e32 v73, 0x3fb8aa3b, v73
	v_exp_f32_e32 v153, v73
	v_add_u32_e32 v73, 32, v82
	v_and_b32_e32 v73, 0x70, v73
	v_add_lshl_u32 v73, v73, v80, 1
	v_and_b32_e32 v73, 0xf8, v73
	v_add3_u32 v73, s66, v129, v73
	ds_read_b64 v[142:143], v73
	v_add_u32_e32 v73, v81, v129
	ds_read_b64 v[136:137], v73
	ds_read_b64_tr_b16 v[74:75], v72 offset:8704
	v_mfma_f32_16x16x32_bf16 v[196:199], v[0:3], v[68:71], 0
	v_add_f32_e64 v148, -v148, 1.0
	v_add_f32_e64 v149, -v149, 1.0
	s_andn2_b64 vcc, exec, s[34:35]
	s_mov_b64 s[30:31], s[18:19]
	s_waitcnt lgkmcnt(0)
	v_lshlrev_b32_e32 v73, 16, v74
	v_mul_f32_e32 v73, 0x3fb8aa3b, v73
	v_exp_f32_e32 v158, v73
	v_and_b32_e32 v73, 0xffff0000, v74
	v_mul_f32_e32 v73, 0x3fb8aa3b, v73
	v_exp_f32_e32 v159, v73
	v_lshlrev_b32_e32 v73, 16, v75
	v_mul_f32_e32 v73, 0x3fb8aa3b, v73
	v_exp_f32_e32 v156, v73
	v_and_b32_e32 v73, 0xffff0000, v75
	v_mul_f32_e32 v73, 0x3fb8aa3b, v73
	v_exp_f32_e32 v157, v73
	v_add_u32_e32 v73, 64, v82
	v_and_b32_e32 v73, 0x70, v73
	v_add_lshl_u32 v73, v73, v80, 1
	v_and_b32_e32 v73, 0xf8, v73
	v_add3_u32 v73, s66, v186, v73
	ds_read_b64 v[134:135], v73
	v_add_u32_e32 v73, v81, v186
	ds_read_b64 v[144:145], v73
	ds_read_b64_tr_b16 v[72:73], v72 offset:13056
	v_mfma_f32_16x16x32_bf16 v[96:99], v[68:71], v[4:7], 0
	s_waitcnt lgkmcnt(0)
	v_lshlrev_b32_e32 v74, 16, v72
	v_and_b32_e32 v72, 0xffff0000, v72
	v_mul_f32_e32 v72, 0x3fb8aa3b, v72
	v_exp_f32_e32 v163, v72
	v_lshlrev_b32_e32 v72, 16, v73
	v_mul_f32_e32 v72, 0x3fb8aa3b, v72
	v_exp_f32_e32 v160, v72
	v_and_b32_e32 v72, 0xffff0000, v73
	v_mul_f32_e32 v72, 0x3fb8aa3b, v72
	v_exp_f32_e32 v161, v72
	v_add_u32_e32 v72, 0x60, v82
	v_and_b32_e32 v72, 0x70, v72
	v_add_lshl_u32 v72, v72, v80, 1
	v_and_b32_e32 v72, 0xf8, v72
	v_add3_u32 v72, s66, v131, v72
	v_mul_f32_e32 v74, 0x3fb8aa3b, v74
	ds_read_b64 v[132:133], v72
	v_add_u32_e32 v72, v81, v131
	v_exp_f32_e32 v162, v74
	ds_read_b64 v[138:139], v72
	v_mov_b64_e32 v[74:75], s[46:47]
	v_mov_b64_e32 v[72:73], s[44:45]
	v_mfma_f32_16x16x32_bf16 v[88:91], v[68:71], v[0:3], 0
	s_nop 0
	v_mfma_f32_16x16x32_bf16 v[80:83], v[72:75], v[68:71], 0
	v_mfma_f32_16x16x32_bf16 v[220:223], v[72:75], v[76:79], v[80:83]
	v_mfma_f32_16x16x32_bf16 v[224:227], v[68:71], v[72:75], 0
	v_mfma_f32_16x16x32_bf16 v[92:95], v[68:71], v[8:11], 0
	s_nop 5
	v_sub_f32_e32 v68, v220, v192
	v_sub_f32_e32 v69, v221, v193
	v_mul_f32_e32 v68, 0x3fb8aa3b, v68
	v_mul_f32_e32 v69, 0x3fb8aa3b, v69
	v_exp_f32_e32 v68, v68
	v_exp_f32_e32 v69, v69
	v_pk_add_f32 v[70:71], v[150:151], 1.0 op_sel_hi:[1,0] neg_lo:[1,0] neg_hi:[1,0]
	v_pk_add_f32 v[150:151], v[154:155], 1.0 op_sel_hi:[1,0] neg_lo:[1,0] neg_hi:[1,0]
	v_mfma_f32_16x16x32_bf16 v[200:203], v[4:7], v[76:79], v[80:83]
	v_mul_f32_e64 v68, v70, v68
	v_mul_f32_e64 v69, v71, v69
	v_sub_f32_e32 v70, v222, v194
	v_sub_f32_e32 v71, v223, v195
	v_mul_f32_e32 v70, 0x3fb8aa3b, v70
	v_mul_f32_e32 v71, 0x3fb8aa3b, v71
	v_exp_f32_e32 v70, v70
	v_exp_f32_e32 v71, v71
	v_mfma_f32_16x16x32_bf16 v[204:207], v[0:3], v[76:79], v[80:83]
	v_sub_f32_e32 v96, v96, v92
	v_sub_f32_e32 v97, v97, v93
	v_pk_mul_f32 v[70:71], v[148:149], v[70:71]
	v_sub_f32_e32 v148, v220, v196
	v_sub_f32_e32 v149, v221, v197
	v_mul_f32_e32 v148, 0x3fb8aa3b, v148
	v_mul_f32_e32 v149, 0x3fb8aa3b, v149
	v_exp_f32_e32 v148, v148
	v_exp_f32_e32 v149, v149
	v_mfma_f32_16x16x32_bf16 v[84:87], v[76:79], v[4:7], v[224:227]
	v_sub_f32_e32 v98, v98, v94
	v_sub_f32_e32 v99, v99, v95
	v_pk_mul_f32 v[154:155], v[150:151], v[148:149]
	v_sub_f32_e32 v148, v222, v198
	v_sub_f32_e32 v149, v223, v199
	v_mul_f32_e32 v148, 0x3fb8aa3b, v148
	v_mul_f32_e32 v149, 0x3fb8aa3b, v149
	v_exp_f32_e32 v148, v148
	v_exp_f32_e32 v149, v149
	v_pk_add_f32 v[150:151], v[152:153], 1.0 op_sel_hi:[1,0] neg_lo:[1,0] neg_hi:[1,0]
	v_mfma_f32_16x16x32_bf16 v[80:83], v[76:79], v[0:3], v[224:227]
	v_med3_f32 v191, v96, s67, v218
	v_pk_mul_f32 v[152:153], v[150:151], v[148:149]
	v_sub_f32_e32 v148, v220, v200
	v_sub_f32_e32 v149, v221, v201
	v_mul_f32_e32 v148, 0x3fb8aa3b, v148
	v_mul_f32_e32 v149, 0x3fb8aa3b, v149
	v_exp_f32_e32 v148, v148
	v_exp_f32_e32 v149, v149
	v_pk_add_f32 v[150:151], v[158:159], 1.0 op_sel_hi:[1,0] neg_lo:[1,0] neg_hi:[1,0]
	v_med3_f32 v194, v97, s67, v218
	v_med3_f32 v195, v98, s67, v218
	v_pk_mul_f32 v[158:159], v[150:151], v[148:149]
	v_sub_f32_e32 v148, v222, v202
	v_sub_f32_e32 v149, v223, v203
	v_mul_f32_e32 v148, 0x3fb8aa3b, v148
	v_mul_f32_e32 v149, 0x3fb8aa3b, v149
	v_exp_f32_e32 v148, v148
	v_exp_f32_e32 v149, v149
	v_pk_add_f32 v[150:151], v[156:157], 1.0 op_sel_hi:[1,0] neg_lo:[1,0] neg_hi:[1,0]
	v_med3_f32 v196, v99, s67, v218
	v_mul_f32_e32 v96, 0x3fb8aa3b, v191
	v_pk_mul_f32 v[156:157], v[150:151], v[148:149]
	v_sub_f32_e32 v148, v220, v204
	v_sub_f32_e32 v149, v221, v205
	v_mul_f32_e32 v148, 0x3fb8aa3b, v148
	v_mul_f32_e32 v149, 0x3fb8aa3b, v149
	v_exp_f32_e32 v148, v148
	v_exp_f32_e32 v149, v149
	v_pk_add_f32 v[150:151], v[162:163], 1.0 op_sel_hi:[1,0] neg_lo:[1,0] neg_hi:[1,0]
	v_mul_f32_e32 v97, 0x3fb8aa3b, v194
	v_mul_f32_e32 v98, 0x3fb8aa3b, v195
	v_pk_mul_f32 v[162:163], v[150:151], v[148:149]
	v_sub_f32_e32 v148, v222, v206
	v_mul_f32_e32 v148, 0x3fb8aa3b, v148
	v_exp_f32_e32 v192, v148
	v_sub_f32_e32 v148, v223, v207
	v_mul_f32_e32 v148, 0x3fb8aa3b, v148
	v_exp_f32_e32 v193, v148
	v_mfma_f32_16x16x32_bf16 v[148:151], v[76:79], v[72:75], v[224:227]
	v_cvt_pk_bf16_f32 v75, v152, v153
	v_pk_add_f32 v[152:153], v[160:161], 1.0 op_sel_hi:[1,0] neg_lo:[1,0] neg_hi:[1,0]
	v_cvt_pk_bf16_f32 v73, v70, v71
	v_mfma_f32_16x16x32_bf16 v[76:79], v[76:79], v[8:11], v[224:227]
	v_mul_f32_e64 v152, v152, v192
	v_mul_f32_e64 v153, v153, v193
	v_cvt_pk_bf16_f32 v74, v154, v155
	v_cvt_pk_bf16_f32 v71, v152, v153
	v_mul_f32_e32 v152, 0x3fb8aa3b, v92
	v_exp_f32_e32 v160, v152
	s_nop 1
	v_mul_f32_e32 v152, 0x3fb8aa3b, v76
	v_exp_f32_e32 v154, v152
	v_sub_f32_e32 v152, v76, v92
	v_mul_f32_e32 v152, 0x3fb8aa3b, v152
	v_cvt_pk_bf16_f32 v72, v68, v69
	v_cvt_pk_bf16_f32 v69, v156, v157
	v_exp_f32_e32 v156, v152
	v_mul_f32_e32 v152, 0x3fb8aa3b, v93
	v_exp_f32_e32 v161, v152
	v_mul_f32_e32 v152, 0x3fb8aa3b, v77
	v_exp_f32_e32 v155, v152
	v_sub_f32_e32 v152, v77, v93
	v_sub_f32_e32 v153, v78, v94
	v_mul_f32_e32 v152, 0x3fb8aa3b, v152
	v_mul_f32_e32 v153, 0x3fb8aa3b, v153
	v_mul_f32_e32 v99, 0x3fb8aa3b, v196
	v_cvt_pk_bf16_f32 v68, v158, v159
	v_exp_f32_e32 v157, v152
	v_mul_f32_e32 v152, 0x3fb8aa3b, v94
	v_exp_f32_e32 v158, v153
	v_mul_f32_e32 v153, 0x3fb8aa3b, v95
	v_exp_f32_e32 v96, v96
	v_exp_f32_e32 v97, v97
	v_exp_f32_e32 v98, v98
	v_exp_f32_e32 v99, v99
	v_cvt_pk_bf16_f32 v70, v162, v163
	v_exp_f32_e32 v162, v152
	v_exp_f32_e32 v163, v153
	v_lshlrev_b32_e32 v192, 16, v146
	v_and_b32_e32 v193, 0xffff0000, v146
	v_lshlrev_b32_e32 v146, 16, v147
	v_and_b32_e32 v147, 0xffff0000, v147
	v_pk_mul_f32 v[96:97], v[96:97], v[192:193]
	v_pk_mul_f32 v[98:99], v[98:99], v[146:147]
	v_pk_mul_f32 v[192:193], v[160:161], v[96:97]
	v_pk_mul_f32 v[146:147], v[162:163], v[98:99]
	v_cvt_pk_bf16_f32 v192, v192, v193
	v_cvt_pk_bf16_f32 v193, v146, v147
	v_cvt_pk_bf16_f32 v96, v96, v97
	v_cvt_pk_bf16_f32 v97, v98, v99
	v_add3_u32 v197, v172, v185, 0
	ds_write2st64_b64 v197, v[192:193], v[96:97] offset1:34
	v_mul_f32_e32 v97, 0xbfb8aa3b, v191
	v_lshlrev_b32_e32 v96, 16, v140
	v_exp_f32_e32 v98, v97
	v_and_b32_e32 v97, 0xffff0000, v140
	v_mul_f32_e32 v96, 0x3fb8aa3b, v96
	v_mul_f32_e32 v97, 0x3fb8aa3b, v97
	v_exp_f32_e32 v96, v96
	v_exp_f32_e32 v97, v97
	v_mul_f32_e32 v99, 0xbfb8aa3b, v194
	v_exp_f32_e32 v99, v99
	v_sub_f32_e32 v159, v79, v95
	v_pk_add_f32 v[96:97], v[96:97], 1.0 op_sel_hi:[1,0] neg_lo:[1,0] neg_hi:[1,0]
	v_mul_f32_e32 v159, 0x3fb8aa3b, v159
	v_pk_mul_f32 v[96:97], v[96:97], v[98:99]
	v_lshlrev_b32_e32 v99, 16, v141
	v_mul_f32_e32 v99, 0x3fb8aa3b, v99
	v_exp_f32_e32 v140, v99
	v_mul_f32_e32 v99, 0xbfb8aa3b, v195
	v_exp_f32_e32 v146, v99
	v_and_b32_e32 v99, 0xffff0000, v141
	v_mul_f32_e32 v99, 0x3fb8aa3b, v99
	v_exp_f32_e32 v141, v99
	v_mul_f32_e32 v99, 0xbfb8aa3b, v196
	v_exp_f32_e32 v147, v99
	v_exp_f32_e32 v159, v159
	v_pk_add_f32 v[140:141], v[140:141], 1.0 op_sel_hi:[1,0] neg_lo:[1,0] neg_hi:[1,0]
	v_cvt_pk_bf16_f32 v98, v96, v97
	v_pk_mul_f32 v[140:141], v[140:141], v[146:147]
	v_pk_mul_f32 v[96:97], v[156:157], v[96:97]
	v_cvt_pk_bf16_f32 v99, v140, v141
	v_pk_mul_f32 v[140:141], v[158:159], v[140:141]
	v_cvt_pk_bf16_f32 v96, v96, v97
	v_cvt_pk_bf16_f32 v97, v140, v141
	v_sub_f32_e32 v88, v88, v92
	v_sub_f32_e32 v89, v89, v93
	v_sub_f32_e32 v90, v90, v94
	v_sub_f32_e32 v91, v91, v95
	ds_write2st64_b64 v197, v[98:99], v[96:97] offset0:68 offset1:85
	v_med3_f32 v96, v88, s67, v218
	v_med3_f32 v97, v89, s67, v218
	v_med3_f32 v98, v90, s67, v218
	v_med3_f32 v99, v91, s67, v218
	v_mul_f32_e32 v88, 0x3fb8aa3b, v96
	v_mul_f32_e32 v89, 0x3fb8aa3b, v97
	v_mul_f32_e32 v90, 0x3fb8aa3b, v98
	v_mul_f32_e32 v91, 0x3fb8aa3b, v99
	v_exp_f32_e32 v88, v88
	v_exp_f32_e32 v89, v89
	v_exp_f32_e32 v90, v90
	v_exp_f32_e32 v91, v91
	v_lshlrev_b32_e32 v92, 16, v142
	v_and_b32_e32 v93, 0xffff0000, v142
	v_lshlrev_b32_e32 v94, 16, v143
	v_and_b32_e32 v95, 0xffff0000, v143
	v_pk_mul_f32 v[88:89], v[88:89], v[92:93]
	v_pk_mul_f32 v[90:91], v[90:91], v[94:95]
	v_pk_mul_f32 v[92:93], v[160:161], v[88:89]
	v_pk_mul_f32 v[94:95], v[162:163], v[90:91]
	v_cvt_pk_bf16_f32 v92, v92, v93
	v_cvt_pk_bf16_f32 v93, v94, v95
	v_cvt_pk_bf16_f32 v88, v88, v89
	v_cvt_pk_bf16_f32 v89, v90, v91
	v_add3_u32 v140, v172, v129, 0
	ds_write2st64_b64 v140, v[92:93], v[88:89] offset1:34
	v_mul_f32_e32 v89, 0xbfb8aa3b, v96
	v_lshlrev_b32_e32 v88, 16, v136
	v_exp_f32_e32 v90, v89
	v_and_b32_e32 v89, 0xffff0000, v136
	v_mul_f32_e32 v88, 0x3fb8aa3b, v88
	v_mul_f32_e32 v89, 0x3fb8aa3b, v89
	v_exp_f32_e32 v88, v88
	v_exp_f32_e32 v89, v89
	v_mul_f32_e32 v91, 0xbfb8aa3b, v97
	v_exp_f32_e32 v91, v91
	v_sub_f32_e32 v84, v84, v76
	v_pk_add_f32 v[88:89], v[88:89], 1.0 op_sel_hi:[1,0] neg_lo:[1,0] neg_hi:[1,0]
	v_sub_f32_e32 v85, v85, v77
	v_pk_mul_f32 v[88:89], v[88:89], v[90:91]
	v_lshlrev_b32_e32 v91, 16, v137
	v_mul_f32_e32 v91, 0x3fb8aa3b, v91
	v_exp_f32_e32 v92, v91
	v_mul_f32_e32 v91, 0xbfb8aa3b, v98
	v_exp_f32_e32 v94, v91
	v_and_b32_e32 v91, 0xffff0000, v137
	v_mul_f32_e32 v91, 0x3fb8aa3b, v91
	v_exp_f32_e32 v93, v91
	v_mul_f32_e32 v91, 0xbfb8aa3b, v99
	v_exp_f32_e32 v95, v91
	v_cvt_pk_bf16_f32 v90, v88, v89
	v_pk_add_f32 v[92:93], v[92:93], 1.0 op_sel_hi:[1,0] neg_lo:[1,0] neg_hi:[1,0]
	v_pk_mul_f32 v[88:89], v[156:157], v[88:89]
	v_pk_mul_f32 v[92:93], v[92:93], v[94:95]
	v_cvt_pk_bf16_f32 v88, v88, v89
	v_cvt_pk_bf16_f32 v91, v92, v93
	v_pk_mul_f32 v[92:93], v[158:159], v[92:93]
	v_sub_f32_e32 v86, v86, v78
	v_cvt_pk_bf16_f32 v89, v92, v93
	ds_write2st64_b64 v140, v[90:91], v[88:89] offset0:68 offset1:85
	v_lshlrev_b32_e32 v88, 16, v144
	v_and_b32_e32 v89, 0xffff0000, v144
	v_mul_f32_e32 v88, 0x3fb8aa3b, v88
	v_mul_f32_e32 v89, 0x3fb8aa3b, v89
	v_med3_f32 v92, v84, s67, v218
	v_med3_f32 v93, v85, s67, v218
	v_exp_f32_e32 v88, v88
	v_exp_f32_e32 v89, v89
	v_mul_f32_e32 v84, 0x3fb8aa3b, v92
	v_mul_f32_e32 v92, 0xbfb8aa3b, v92
	v_mul_f32_e32 v85, 0x3fb8aa3b, v93
	v_mul_f32_e32 v93, 0xbfb8aa3b, v93
	v_exp_f32_e32 v92, v92
	v_exp_f32_e32 v93, v93
	v_pk_add_f32 v[88:89], v[88:89], 1.0 op_sel_hi:[1,0] neg_lo:[1,0] neg_hi:[1,0]
	v_sub_f32_e32 v87, v87, v79
	v_lshlrev_b32_e32 v90, 16, v145
	v_pk_mul_f32 v[88:89], v[88:89], v[92:93]
	v_med3_f32 v92, v86, s67, v218
	v_med3_f32 v93, v87, s67, v218
	v_and_b32_e32 v91, 0xffff0000, v145
	v_mul_f32_e32 v86, 0x3fb8aa3b, v92
	v_mul_f32_e32 v87, 0x3fb8aa3b, v93
	v_mul_f32_e32 v152, 0x3fb8aa3b, v78
	v_mul_f32_e32 v153, 0x3fb8aa3b, v79
	v_mul_f32_e32 v90, 0x3fb8aa3b, v90
	v_mul_f32_e32 v91, 0x3fb8aa3b, v91
	v_exp_f32_e32 v84, v84
	v_exp_f32_e32 v85, v85
	v_exp_f32_e32 v86, v86
	v_exp_f32_e32 v87, v87
	v_exp_f32_e32 v152, v152
	v_exp_f32_e32 v153, v153
	v_exp_f32_e32 v90, v90
	v_exp_f32_e32 v91, v91
	v_mul_f32_e32 v92, 0xbfb8aa3b, v92
	v_mul_f32_e32 v93, 0xbfb8aa3b, v93
	v_exp_f32_e32 v92, v92
	v_exp_f32_e32 v93, v93
	v_lshlrev_b32_e32 v94, 16, v134
	v_and_b32_e32 v95, 0xffff0000, v134
	v_lshlrev_b32_e32 v96, 16, v135
	v_and_b32_e32 v97, 0xffff0000, v135
	v_pk_mul_f32 v[84:85], v[84:85], v[94:95]
	v_pk_mul_f32 v[86:87], v[86:87], v[96:97]
	v_pk_mul_f32 v[94:95], v[154:155], v[84:85]
	v_pk_mul_f32 v[96:97], v[152:153], v[86:87]
	v_pk_add_f32 v[90:91], v[90:91], 1.0 op_sel_hi:[1,0] neg_lo:[1,0] neg_hi:[1,0]
	v_cvt_pk_bf16_f32 v84, v84, v85
	v_pk_mul_f32 v[90:91], v[90:91], v[92:93]
	v_cvt_pk_bf16_f32 v92, v94, v95
	v_cvt_pk_bf16_f32 v93, v96, v97
	v_cvt_pk_bf16_f32 v85, v86, v87
	v_cvt_pk_bf16_f32 v86, v88, v89
	v_add3_u32 v88, v172, v186, 0
	v_cvt_pk_bf16_f32 v87, v90, v91
	ds_write2st64_b64 v88, v[92:93], v[84:85] offset1:34
	ds_write_b64 v88, v[86:87] offset:43520
	s_waitcnt lgkmcnt(6)
	v_lshlrev_b32_e32 v84, 16, v138
	v_and_b32_e32 v85, 0xffff0000, v138
	v_sub_f32_e32 v76, v80, v76
	v_sub_f32_e32 v77, v81, v77
	v_mul_f32_e32 v84, 0x3fb8aa3b, v84
	v_mul_f32_e32 v85, 0x3fb8aa3b, v85
	v_med3_f32 v80, v76, s67, v218
	v_med3_f32 v81, v77, s67, v218
	v_sub_f32_e32 v78, v82, v78
	v_sub_f32_e32 v79, v83, v79
	v_exp_f32_e32 v84, v84
	v_exp_f32_e32 v85, v85
	v_mul_f32_e32 v76, 0x3fb8aa3b, v80
	v_mul_f32_e32 v80, 0xbfb8aa3b, v80
	v_mul_f32_e32 v77, 0x3fb8aa3b, v81
	v_mul_f32_e32 v81, 0xbfb8aa3b, v81
	v_med3_f32 v82, v78, s67, v218
	v_med3_f32 v83, v79, s67, v218
	v_lshlrev_b32_e32 v86, 16, v139
	v_and_b32_e32 v87, 0xffff0000, v139
	v_exp_f32_e32 v80, v80
	v_exp_f32_e32 v81, v81
	v_mul_f32_e32 v78, 0x3fb8aa3b, v82
	v_mul_f32_e32 v79, 0x3fb8aa3b, v83
	v_mul_f32_e32 v86, 0x3fb8aa3b, v86
	v_mul_f32_e32 v87, 0x3fb8aa3b, v87
	v_exp_f32_e32 v76, v76
	v_exp_f32_e32 v77, v77
	v_exp_f32_e32 v78, v78
	v_exp_f32_e32 v79, v79
	v_exp_f32_e32 v86, v86
	v_exp_f32_e32 v87, v87
	v_mul_f32_e32 v82, 0xbfb8aa3b, v82
	v_mul_f32_e32 v83, 0xbfb8aa3b, v83
	v_pk_add_f32 v[84:85], v[84:85], 1.0 op_sel_hi:[1,0] neg_lo:[1,0] neg_hi:[1,0]
	v_exp_f32_e32 v82, v82
	v_exp_f32_e32 v83, v83
	v_lshlrev_b32_e32 v88, 16, v132
	v_and_b32_e32 v89, 0xffff0000, v132
	v_pk_mul_f32 v[80:81], v[84:85], v[80:81]
	v_lshlrev_b32_e32 v84, 16, v133
	v_and_b32_e32 v85, 0xffff0000, v133
	v_pk_mul_f32 v[76:77], v[76:77], v[88:89]
	v_pk_mul_f32 v[78:79], v[78:79], v[84:85]
	v_pk_mul_f32 v[88:89], v[154:155], v[76:77]
	v_pk_mul_f32 v[84:85], v[152:153], v[78:79]
	v_pk_add_f32 v[86:87], v[86:87], 1.0 op_sel_hi:[1,0] neg_lo:[1,0] neg_hi:[1,0]
	v_cvt_pk_bf16_f32 v76, v76, v77
	v_pk_mul_f32 v[82:83], v[86:87], v[82:83]
	v_cvt_pk_bf16_f32 v86, v88, v89
	v_cvt_pk_bf16_f32 v87, v84, v85
	v_cvt_pk_bf16_f32 v77, v78, v79
	v_cvt_pk_bf16_f32 v78, v80, v81
	v_add3_u32 v80, v172, v131, 0
	v_cvt_pk_bf16_f32 v79, v82, v83
	ds_write2st64_b64 v80, v[86:87], v[76:77] offset1:34
	ds_write_b64 v80, v[78:79] offset:43520
	v_lshlrev_b32_e32 v92, 1, v189
	v_mul_lo_u32 v76, v190, s20
	v_mul_f32_e32 v148, 0x3fb8aa3b, v148
	v_mul_f32_e32 v149, 0x3fb8aa3b, v149
	v_mul_f32_e32 v150, 0x3fb8aa3b, v150
	v_mul_f32_e32 v151, 0x3fb8aa3b, v151
	s_waitcnt lgkmcnt(0)
	s_barrier
	v_add3_u32 v84, s60, v92, v76
	v_exp_f32_e32 v148, v148
	v_exp_f32_e32 v149, v149
	v_exp_f32_e32 v150, v150
	v_exp_f32_e32 v151, v151
	ds_read_b64_tr_b16 v[76:77], v84
	ds_read_b64_tr_b16 v[80:81], v84 offset:32
	ds_read_b64_tr_b16 v[78:79], v84 offset:4608
	v_pk_mul_f32 v[12:13], v[12:13], v[148:149]
	v_pk_mul_f32 v[16:17], v[16:17], v[148:149]
	v_pk_mul_f32 v[14:15], v[14:15], v[150:151]
	v_pk_mul_f32 v[18:19], v[18:19], v[150:151]
	v_pk_mul_f32 v[26:27], v[26:27], v[150:151]
	s_waitcnt lgkmcnt(0)
	v_mfma_f32_16x16x32_bf16 v[12:15], v[72:75], v[76:79], v[12:15]
	ds_read_b64_tr_b16 v[76:77], v84 offset:9216
	ds_read_b64_tr_b16 v[78:79], v84 offset:13824
	ds_read_b64_tr_b16 v[82:83], v84 offset:4640
	v_pk_mul_f32 v[24:25], v[24:25], v[148:149]
	s_waitcnt lgkmcnt(1)
	v_mfma_f32_16x16x32_bf16 v[12:15], v[68:71], v[76:79], v[12:15]
	ds_read_b64_tr_b16 v[76:77], v84 offset:9248
	ds_read_b64_tr_b16 v[78:79], v84 offset:13856
	v_pk_mul_f32 v[34:35], v[34:35], v[150:151]
	v_pk_mul_f32 v[32:33], v[32:33], v[148:149]
	s_waitcnt lgkmcnt(2)
	v_mfma_f32_16x16x32_bf16 v[16:19], v[72:75], v[80:83], v[16:19]
	v_mul_f32_e64 v22, v22, v150
	v_mul_f32_e64 v23, v23, v151
	v_pk_mul_f32 v[20:21], v[20:21], v[148:149]
	v_pk_mul_f32 v[30:31], v[30:31], v[150:151]
	s_waitcnt lgkmcnt(0)
	v_mfma_f32_16x16x32_bf16 v[16:19], v[68:71], v[76:79], v[16:19]
	ds_read_b64_tr_b16 v[76:77], v84 offset:64
	ds_read_b64_tr_b16 v[78:79], v84 offset:4672
	ds_read_b64_tr_b16 v[228:229], v84 offset:9280
	ds_read_b64_tr_b16 v[230:231], v84 offset:13888
	ds_read_b64_tr_b16 v[232:233], v84 offset:96
	ds_read_b64_tr_b16 v[234:235], v84 offset:4704
	ds_read_b64_tr_b16 v[236:237], v84 offset:9312
	ds_read_b64_tr_b16 v[238:239], v84 offset:13920
	v_pk_mul_f32 v[28:29], v[28:29], v[148:149]
	v_pk_mul_f32 v[38:39], v[38:39], v[150:151]
	s_waitcnt lgkmcnt(6)
	v_mfma_f32_16x16x32_bf16 v[24:27], v[72:75], v[76:79], v[24:27]
	ds_read_b64_tr_b16 v[76:77], v84 offset:128
	ds_read_b64_tr_b16 v[78:79], v84 offset:4736
	v_pk_mul_f32 v[36:37], v[36:37], v[148:149]
	v_pk_mul_f32 v[42:43], v[42:43], v[150:151]
	s_waitcnt lgkmcnt(6)
	v_mfma_f32_16x16x32_bf16 v[24:27], v[68:71], v[228:231], v[24:27]
	ds_read_b64_tr_b16 v[228:229], v84 offset:9344
	ds_read_b64_tr_b16 v[230:231], v84 offset:13952
	v_pk_mul_f32 v[40:41], v[40:41], v[148:149]
	v_lshlrev_b32_e32 v95, 4, v187
	s_waitcnt lgkmcnt(6)
	v_mfma_f32_16x16x32_bf16 v[32:35], v[72:75], v[232:235], v[32:35]
	ds_read_b64_tr_b16 v[232:233], v84 offset:160
	ds_read_b64_tr_b16 v[234:235], v84 offset:4768
	v_add_u32_e32 v89, s84, v95
	v_add_u32_e32 v90, v89, v185
	s_waitcnt lgkmcnt(6)
	v_mfma_f32_16x16x32_bf16 v[32:35], v[68:71], v[236:239], v[32:35]
	ds_read_b64_tr_b16 v[236:237], v84 offset:9376
	ds_read_b64_tr_b16 v[238:239], v84 offset:13984
	s_waitcnt lgkmcnt(6)
	v_mfma_f32_16x16x32_bf16 v[20:23], v[72:75], v[76:79], v[20:23]
	ds_read_b64_tr_b16 v[76:77], v84 offset:192
	ds_read_b64_tr_b16 v[78:79], v84 offset:4800
	s_waitcnt lgkmcnt(6)
	v_mfma_f32_16x16x32_bf16 v[20:23], v[68:71], v[228:231], v[20:23]
	ds_read_b64_tr_b16 v[228:229], v84 offset:9408
	ds_read_b64_tr_b16 v[230:231], v84 offset:14016
	s_waitcnt lgkmcnt(6)
	v_mfma_f32_16x16x32_bf16 v[28:31], v[72:75], v[232:235], v[28:31]
	ds_read_b64_tr_b16 v[232:233], v84 offset:224
	ds_read_b64_tr_b16 v[234:235], v84 offset:4832
	s_waitcnt lgkmcnt(6)
	v_mfma_f32_16x16x32_bf16 v[28:31], v[68:71], v[236:239], v[28:31]
	s_waitcnt lgkmcnt(4)
	v_mfma_f32_16x16x32_bf16 v[36:39], v[72:75], v[76:79], v[36:39]
	s_waitcnt lgkmcnt(2)
	v_mfma_f32_16x16x32_bf16 v[36:39], v[68:71], v[228:231], v[36:39]
	s_waitcnt lgkmcnt(0)
	v_mfma_f32_16x16x32_bf16 v[40:43], v[72:75], v[232:235], v[40:43]
	ds_read_b64_tr_b16 v[72:73], v84 offset:9440
	ds_read_b64_tr_b16 v[74:75], v84 offset:14048
	s_waitcnt lgkmcnt(0)
	v_mfma_f32_16x16x32_bf16 v[40:43], v[68:71], v[72:75], v[40:43]
	v_add_u32_e32 v68, s85, v128
	v_mul_lo_u32 v68, v68, s61
	v_add_u32_e32 v68, 0, v68
	v_add_u32_e32 v88, v68, v95
	ds_read_b128 v[80:83], v88 offset:17408
	ds_read_b128 v[84:87], v88 offset:17472
	ds_read_b128 v[96:99], v88 offset:17536
	ds_read_b128 v[132:135], v88 offset:17600
	ds_read_b128 v[68:71], v90
	ds_read_b128 v[72:75], v90 offset:64
	ds_read_b128 v[76:79], v90 offset:128
	ds_read_b128 v[136:139], v90 offset:192
	s_waitcnt lgkmcnt(3)
	v_mfma_f32_16x16x32_bf16 v[68:71], v[68:71], v[80:83], 0
	v_add_u32_e32 v90, v89, v129
	s_waitcnt lgkmcnt(2)
	v_mfma_f32_16x16x32_bf16 v[68:71], v[72:75], v[84:87], v[68:71]
	s_waitcnt lgkmcnt(1)
	v_mfma_f32_16x16x32_bf16 v[68:71], v[76:79], v[96:99], v[68:71]
	s_waitcnt lgkmcnt(0)
	v_mfma_f32_16x16x32_bf16 v[68:71], v[136:139], v[132:135], v[68:71]
	ds_read_b128 v[72:75], v90
	ds_read_b128 v[76:79], v90 offset:64
	ds_read_b128 v[136:139], v90 offset:128
	ds_read_b128 v[140:143], v90 offset:192
	v_add_u32_e32 v90, v89, v186
	v_add_u32_e32 v89, v89, v131
	s_waitcnt lgkmcnt(3)
	v_mfma_f32_16x16x32_bf16 v[72:75], v[72:75], v[80:83], 0
	s_waitcnt lgkmcnt(2)
	v_mfma_f32_16x16x32_bf16 v[72:75], v[76:79], v[84:87], v[72:75]
	s_waitcnt lgkmcnt(1)
	v_mfma_f32_16x16x32_bf16 v[72:75], v[136:139], v[96:99], v[72:75]
	s_waitcnt lgkmcnt(0)
	v_mfma_f32_16x16x32_bf16 v[72:75], v[140:143], v[132:135], v[72:75]
	ds_read_b128 v[76:79], v90
	ds_read_b128 v[136:139], v90 offset:64
	ds_read_b128 v[140:143], v90 offset:128
	ds_read_b128 v[144:147], v90 offset:192
	s_waitcnt lgkmcnt(3)
	v_mfma_f32_16x16x32_bf16 v[76:79], v[76:79], v[80:83], 0
	s_waitcnt lgkmcnt(2)
	v_mfma_f32_16x16x32_bf16 v[76:79], v[136:139], v[84:87], v[76:79]
	s_waitcnt lgkmcnt(1)
	v_mfma_f32_16x16x32_bf16 v[76:79], v[140:143], v[96:99], v[76:79]
	s_waitcnt lgkmcnt(0)
	v_mfma_f32_16x16x32_bf16 v[76:79], v[144:147], v[132:135], v[76:79]
	ds_read_b128 v[136:139], v89
	ds_read_b128 v[140:143], v89 offset:64
	ds_read_b128 v[144:147], v89 offset:128
	ds_read_b128 v[148:151], v89 offset:192
	s_waitcnt lgkmcnt(3)
	v_mfma_f32_16x16x32_bf16 v[80:83], v[136:139], v[80:83], 0
	s_waitcnt lgkmcnt(2)
	v_mfma_f32_16x16x32_bf16 v[80:83], v[140:143], v[84:87], v[80:83]
	v_cndmask_b32_e64 v84, 0, 1, s[34:35]
	v_or_b32_e32 v85, 2, v130
	v_cmp_ne_u32_e64 s[0:1], 1, v84
	s_waitcnt lgkmcnt(1)
	v_mfma_f32_16x16x32_bf16 v[80:83], v[144:147], v[96:99], v[80:83]
	v_cmp_le_i32_e64 s[36:37], v85, v128
	s_waitcnt lgkmcnt(0)
	v_mfma_f32_16x16x32_bf16 v[80:83], v[148:151], v[132:135], v[80:83]
	s_cbranch_vccnz .LBB0_608
	s_and_b64 s[30:31], s[38:39], s[36:37]
	s_andn2_b64 s[36:37], s[18:19], exec
	s_and_b64 s[30:31], s[30:31], exec
	s_or_b64 s[30:31], s[36:37], s[30:31]
